# row-wise norm loops (h1, x1, final): all per-row global loads hoisted to the loop top with renamed registers and counted vmcnt waits (were serialised behind stores)
# speedup vs baseline: 1.0578x; 1.0129x over previous
; DI int tidx() { int t = threadIdx.x; asm volatile("" : "+v"(t)); return t; }
; DI int bidx() { int b = blockIdx.x; asm volatile("" : "+s"(b)); return b; }
; DI void modnorm_store(const float (&x)[16], int lane, const float* g, const float* sc, const float* sh, bf16_t* dst) {
;   float ss = 0.f;
; #pragma unroll
;   for (int i = 0; i < 16; ++i) ss += x[i] * x[i];
;   ss = wave_sum(ss);
;   const float rstd = rsqrtf(ss * (1.0f / 1024.0f) + 1e-6f);
; #pragma unroll
;   for (int j = 0; j < 4; ++j) {
;     const int c = j * 256 + lane * 4;
;     const float4 gg = *(const float4*)(g + c), s1 = *(const float4*)(sc + c), s0 = *(const float4*)(sh + c);
;     store_bf4(dst + c, x[j * 4] * rstd * gg.x * (1.f + s1.x) + s0.x, x[j * 4 + 1] * rstd * gg.y * (1.f + s1.y) + s0.y,
;               x[j * 4 + 2] * rstd * gg.z * (1.f + s1.z) + s0.z, x[j * 4 + 3] * rstd * gg.w * (1.f + s1.w) + s0.w);
;   }
; }
; DI void phase_h1(const Params& p, int hf) {
;   if (bidx() == 0 && tidx() < 64) ((float*)(p.ws + OFF_KMAX))[tidx()] = 0.f;
;   const int lane = tidx() & 63, gw = bidx() * 8 + (tidx() >> 6), nw = gridDim.x * 8;
;   const int lsh = hf == 0 ? 14 : 13;
;   const float* mod = (const float*)(p.ws + OFF_MOD);
;   bf16_t* h1 = (bf16_t*)(p.ws + OFF_H1);
;   for (int row = gw; row < HALF_TOK; row += nw) {
;     const int b = (hf == 0 ? 0 : 2) + (row >> lsh);
;     float x[16]; load_row16(p.x[hf] + (size_t)row * 1024, lane, x);
;     modnorm_store(x, lane, p.g_pre_mix, mod + b * 6144 + 1024, mod + b * 6144, h1 + (size_t)row * 1024);
;   }
.LBB0_121:
	global_load_dwordx4 v[20:23], v[2:3], off offset:-2048
	global_load_dwordx4 v[24:27], v[2:3], off offset:-1024
	global_load_dwordx4 v[28:31], v[0:1], off
	global_load_dwordx4 v[32:35], v[2:3], off
	global_load_dwordx4 v[36:39], v[2:3], off offset:1024
	v_ashrrev_i32_e32 v19, s14, v12
	v_add_u32_e32 v19, s0, v19
	v_mul_lo_u32 v40, v19, s77
	v_ashrrev_i32_e32 v41, 31, v40
	v_lshl_add_u64 v[40:41], v[40:41], 2, s[56:57]
	v_lshl_add_u64 v[48:49], v[40:41], 0, s[42:43]
	v_lshl_add_u64 v[50:51], v[40:41], 0, v[152:153]
	v_lshl_add_u64 v[40:41], v[48:49], 0, v[152:153]
	global_load_dwordx4 v[40:43], v[40:41], off
	s_nop 0
	global_load_dwordx4 v[44:47], v[50:51], off
	v_lshl_add_u64 v[52:53], v[48:49], 0, v[6:7]
	v_add_u32_e32 v12, s58, v12
	v_lshl_add_u64 v[2:3], v[2:3], 0, s[90:91]
	global_load_dwordx4 v[100:103], v[0:1], off offset:1024
	global_load_dwordx4 v[104:107], v[52:53], off
	global_load_dwordx4 v[108:111], v[50:51], off offset:1024
	v_lshl_add_u64 v[112:113], v[48:49], 0, v[8:9]
	global_load_dwordx4 v[116:119], v[0:1], off offset:2048
	global_load_dwordx4 v[120:123], v[112:113], off
	global_load_dwordx4 v[124:127], v[50:51], off offset:2048
	v_lshl_add_u64 v[114:115], v[48:49], 0, v[10:11]
	global_load_dwordx4 v[128:131], v[0:1], off offset:3072
	global_load_dwordx4 v[132:135], v[114:115], off
	global_load_dwordx4 v[136:139], v[50:51], off offset:3072
	s_waitcnt vmcnt(14)
	v_pk_mul_f32 v[60:61], v[24:25], v[24:25]
	v_pk_mul_f32 v[58:59], v[26:27], v[26:27]
	v_pk_mul_f32 v[56:57], v[20:21], v[20:21]
	v_pk_mul_f32 v[54:55], v[22:23], v[22:23]
	v_add_f32_e32 v19, v56, v57
	v_add_f32_e32 v19, v19, v54
	v_add_f32_e32 v19, v19, v55
	v_add_f32_e32 v19, v19, v60
	v_add_f32_e32 v19, v19, v61
	v_add_f32_e32 v19, v19, v58
	s_waitcnt vmcnt(12)
	v_pk_mul_f32 v[64:65], v[32:33], v[32:33]
	v_add_f32_e32 v19, v19, v59
	v_add_f32_e32 v19, v19, v64
	v_pk_mul_f32 v[62:63], v[34:35], v[34:35]
	v_add_f32_e32 v19, v19, v65
	v_add_f32_e32 v19, v19, v62
	s_waitcnt vmcnt(11)
	v_pk_mul_f32 v[68:69], v[36:37], v[36:37]
	v_add_f32_e32 v19, v19, v63
	v_add_f32_e32 v19, v19, v68
	v_pk_mul_f32 v[66:67], v[38:39], v[38:39]
	v_add_f32_e32 v19, v19, v69
	v_add_f32_e32 v19, v19, v66
	v_add_f32_e32 v19, v19, v67
	ds_bpermute_b32 v54, v13, v19
	s_waitcnt vmcnt(10)
	v_pk_add_f32 v[40:41], v[40:41], 1.0 op_sel_hi:[1, 0]
	v_pk_add_f32 v[42:43], v[42:43], 1.0 op_sel_hi:[1, 0]
	s_waitcnt lgkmcnt(0)
	v_add_f32_e32 v19, v19, v54
	ds_bpermute_b32 v54, v14, v19
	s_waitcnt lgkmcnt(0)
	v_add_f32_e32 v19, v19, v54
	ds_bpermute_b32 v54, v15, v19
	s_waitcnt lgkmcnt(0)
	v_add_f32_e32 v19, v19, v54
	ds_bpermute_b32 v54, v16, v19
	s_waitcnt lgkmcnt(0)
	v_add_f32_e32 v19, v19, v54
	ds_bpermute_b32 v54, v17, v19
	s_waitcnt lgkmcnt(0)
	v_add_f32_e32 v19, v19, v54
	ds_bpermute_b32 v54, v18, v19
	s_waitcnt lgkmcnt(0)
	v_add_f32_e32 v19, v19, v54
	v_fmamk_f32 v19, v19, 0x3a800000, v163
	v_mul_f32_e32 v54, 0x4b800000, v19
	v_cmp_gt_f32_e32 vcc, s21, v19
	s_nop 1
	v_cndmask_b32_e32 v19, v19, v54, vcc
	v_rsq_f32_e32 v19, v19
	s_nop 0
	v_mul_f32_e32 v54, 0x45800000, v19
	v_cndmask_b32_e32 v54, v19, v54, vcc
	v_pk_mul_f32 v[20:21], v[20:21], v[54:55] op_sel_hi:[1, 0]
	v_pk_mul_f32 v[22:23], v[22:23], v[54:55] op_sel_hi:[1, 0]
	v_pk_mul_f32 v[20:21], v[28:29], v[20:21]
	v_pk_mul_f32 v[22:23], v[30:31], v[22:23]
	s_waitcnt vmcnt(9)
	v_pk_fma_f32 v[20:21], v[40:41], v[20:21], v[44:45]
	v_pk_fma_f32 v[22:23], v[42:43], v[22:23], v[46:47]
	v_cvt_pk_bf16_f32 v20, v20, v21
	v_cvt_pk_bf16_f32 v21, v22, v23
	global_store_dwordx2 v[4:5], v[20:21], off offset:-1024
	s_nop 0
	v_pk_mul_f32 v[24:25], v[24:25], v[54:55] op_sel_hi:[1, 0]
	v_pk_mul_f32 v[26:27], v[26:27], v[54:55] op_sel_hi:[1, 0]
	v_pk_mul_f32 v[32:33], v[32:33], v[54:55] op_sel_hi:[1, 0]
	v_pk_mul_f32 v[34:35], v[34:35], v[54:55] op_sel_hi:[1, 0]
	v_cmp_lt_i32_e32 vcc, s96, v12
	s_or_b64 s[8:9], vcc, s[8:9]
	s_waitcnt vmcnt(9)
	v_pk_mul_f32 v[20:21], v[24:25], v[100:101]
	s_waitcnt vmcnt(8)
	v_pk_add_f32 v[24:25], v[104:105], 1.0 op_sel_hi:[1, 0]
	v_pk_mul_f32 v[22:23], v[26:27], v[102:103]
	v_pk_add_f32 v[26:27], v[106:107], 1.0 op_sel_hi:[1, 0]
	s_waitcnt vmcnt(7)
	v_pk_fma_f32 v[20:21], v[20:21], v[24:25], v[108:109]
	v_pk_fma_f32 v[22:23], v[22:23], v[26:27], v[110:111]
	v_cvt_pk_bf16_f32 v20, v20, v21
	v_cvt_pk_bf16_f32 v21, v22, v23
	global_store_dwordx2 v[4:5], v[20:21], off offset:-512
	s_nop 0
	s_waitcnt vmcnt(7)
	v_pk_mul_f32 v[20:21], v[32:33], v[116:117]
	s_waitcnt vmcnt(6)
	v_pk_add_f32 v[24:25], v[120:121], 1.0 op_sel_hi:[1, 0]
	v_pk_mul_f32 v[22:23], v[34:35], v[118:119]
	v_pk_add_f32 v[26:27], v[122:123], 1.0 op_sel_hi:[1, 0]
	s_waitcnt vmcnt(5)
	v_pk_fma_f32 v[20:21], v[20:21], v[24:25], v[124:125]
	v_pk_fma_f32 v[22:23], v[22:23], v[26:27], v[126:127]
	v_cvt_pk_bf16_f32 v20, v20, v21
	v_cvt_pk_bf16_f32 v21, v22, v23
	global_store_dwordx2 v[4:5], v[20:21], off
	s_nop 0
	v_pk_mul_f32 v[32:33], v[36:37], v[54:55] op_sel_hi:[1, 0]
	v_pk_mul_f32 v[34:35], v[38:39], v[54:55] op_sel_hi:[1, 0]
	s_waitcnt vmcnt(5)
	v_pk_mul_f32 v[20:21], v[32:33], v[128:129]
	s_waitcnt vmcnt(4)
	v_pk_add_f32 v[24:25], v[132:133], 1.0 op_sel_hi:[1, 0]
	v_pk_mul_f32 v[22:23], v[34:35], v[130:131]
	v_pk_add_f32 v[26:27], v[134:135], 1.0 op_sel_hi:[1, 0]
	s_waitcnt vmcnt(3)
	v_pk_fma_f32 v[20:21], v[20:21], v[24:25], v[136:137]
	v_pk_fma_f32 v[22:23], v[22:23], v[26:27], v[138:139]
	v_cvt_pk_bf16_f32 v20, v20, v21
	v_cvt_pk_bf16_f32 v21, v22, v23
	global_store_dwordx2 v[4:5], v[20:21], off offset:512
	v_lshl_add_u64 v[4:5], v[4:5], 0, s[84:85]
	s_andn2_b64 exec, exec, s[8:9]
	s_cbranch_execnz .LBB0_121

; DI void phase_x1(const Params& p, int hf) {
;     ...
;   for (int row = gw; row < HALF_TOK; row += nw) {
;     const int b = (hf == 0 ? 0 : 2) + (row >> lsh);
;     const float* mb = mod + b * 6144;
;     float x[16], m[16];
;     load_row16(p.x[hf] + (size_t)row * 1024, lane, x);
;     load_row16_bf(mix + (size_t)row * 1024, lane, m);
;     float ss = 0.f;
; #pragma unroll
;     for (int i = 0; i < 16; ++i) ss += m[i] * m[i];
;     ss = wave_sum(ss);
;     const float rstd = rsqrtf(ss * (1.0f / 1024.0f) + 1e-6f);
; #pragma unroll
;     for (int j = 0; j < 4; ++j) {
;       const int c = j * 256 + lane * 4;
;       const float4 gg = *(const float4*)(p.g_post_mix + c), gt = *(const float4*)(mb + 2048 + c);
;       x[j * 4] += gt.x * m[j * 4] * rstd * gg.x; x[j * 4 + 1] += gt.y * m[j * 4 + 1] * rstd * gg.y;
;       x[j * 4 + 2] += gt.z * m[j * 4 + 2] * rstd * gg.z; x[j * 4 + 3] += gt.w * m[j * 4 + 3] * rstd * gg.w;
;       *(float4*)(outp + (size_t)row * 1024 + c) = make_float4(x[j * 4], x[j * 4 + 1], x[j * 4 + 2], x[j * 4 + 3]);
;     }
;     modnorm_store(x, lane, p.g_pre_ffn, mb + 4096, mb + 3072, h2 + (size_t)row * 1024);
.LBB0_325:
	global_load_dwordx2 v[2:3], v[16:17], off
	v_ashrrev_i32_e32 v0, s14, v40
	v_add_u32_e32 v0, s0, v0
	v_mul_lo_u32 v0, v0, s77
	v_ashrrev_i32_e32 v1, 31, v0
	v_lshl_add_u64 v[30:31], v[0:1], 2, s[56:57]
	v_lshl_add_u64 v[62:63], v[30:31], 0, s[78:79]
	v_lshl_add_u64 v[60:61], v[20:21], 0, v[18:19]
	v_lshl_add_u64 v[0:1], v[62:63], 0, v[152:153]
	global_load_dwordx4 v[48:51], v[60:61], off
	v_lshl_add_u64 v[36:37], v[22:23], 0, v[18:19]
	v_mov_b32_e32 v25, v153
	v_mov_b32_e32 v27, v153
	v_mov_b32_e32 v29, v153
	v_lshl_add_u64 v[72:73], v[62:63], 0, v[24:25]
	v_lshl_add_u64 v[78:79], v[62:63], 0, v[26:27]
	s_mov_b64 s[22:23], 0x4000
	s_brev_b32 s1, 47
	v_add_u32_e32 v40, s58, v40
	v_lshl_add_u64 v[20:21], v[20:21], 0, s[90:91]
	v_lshl_add_u64 v[22:23], v[22:23], 0, s[90:91]
	global_load_dwordx2 v[100:101], v[16:17], off offset:512
	global_load_dwordx2 v[102:103], v[16:17], off offset:1024
	global_load_dwordx2 v[104:105], v[16:17], off offset:1536
	global_load_dwordx4 v[108:111], v[12:13], off
	global_load_dwordx4 v[112:115], v[0:1], off
	global_load_dwordx4 v[116:119], v[60:61], off offset:1024
	global_load_dwordx4 v[120:123], v[60:61], off offset:2048
	v_lshl_add_u64 v[106:107], v[62:63], 0, v[28:29]
	global_load_dwordx4 v[124:127], v[60:61], off offset:3072
	global_load_dwordx4 v[128:131], v[12:13], off offset:1024
	global_load_dwordx4 v[132:135], v[72:73], off
	global_load_dwordx4 v[136:139], v[12:13], off offset:2048
	global_load_dwordx4 v[140:143], v[78:79], off
	global_load_dwordx4 v[144:147], v[12:13], off offset:3072
	global_load_dwordx4 v[148:151], v[106:107], off
	v_lshl_add_u64 v[184:185], v[30:31], 0, s[22:23]
	v_lshl_add_u64 v[186:187], v[184:185], 0, v[152:153]
	global_load_dwordx4 v[188:191], v[14:15], off
	global_load_dwordx4 v[192:195], v[186:187], off
	v_lshl_add_u64 v[196:197], v[184:185], 0, v[24:25]
	global_load_dwordx4 v[200:203], v[14:15], off offset:1024
	global_load_dwordx4 v[204:207], v[196:197], off
	v_lshl_add_u64 v[198:199], v[184:185], 0, v[26:27]
	global_load_dwordx4 v[208:211], v[14:15], off offset:2048
	global_load_dwordx4 v[212:215], v[198:199], off
	v_lshl_add_u64 v[216:217], v[184:185], 0, v[28:29]
	global_load_dwordx4 v[220:223], v[14:15], off offset:3072
	global_load_dwordx4 v[224:227], v[216:217], off
	s_waitcnt vmcnt(23)
	v_lshlrev_b32_e32 v38, 16, v2
	v_and_b32_e32 v39, 0xffff0000, v2
	v_lshlrev_b32_e32 v56, 16, v3
	v_and_b32_e32 v57, 0xffff0000, v3
	v_pk_mul_f32 v[64:65], v[38:39], v[38:39]
	v_pk_mul_f32 v[68:69], v[56:57], v[56:57]
	v_add_f32_e32 v47, v64, v65
	v_add_f32_e32 v47, v47, v68
	v_add_f32_e32 v47, v69, v47
	s_waitcnt vmcnt(21)
	v_lshlrev_b32_e32 v8, 16, v100
	v_and_b32_e32 v9, 0xffff0000, v100
	v_lshlrev_b32_e32 v10, 16, v101
	v_and_b32_e32 v11, 0xffff0000, v101
	v_pk_mul_f32 v[74:75], v[8:9], v[8:9]
	v_pk_mul_f32 v[76:77], v[10:11], v[10:11]
	v_add_f32_e32 v47, v74, v47
	v_add_f32_e32 v47, v75, v47
	v_add_f32_e32 v47, v76, v47
	v_add_f32_e32 v47, v77, v47
	s_waitcnt vmcnt(20)
	v_lshlrev_b32_e32 v4, 16, v102
	v_and_b32_e32 v5, 0xffff0000, v102
	v_lshlrev_b32_e32 v6, 16, v103
	v_and_b32_e32 v7, 0xffff0000, v103
	v_pk_mul_f32 v[80:81], v[4:5], v[4:5]
	v_pk_mul_f32 v[82:83], v[6:7], v[6:7]
	v_add_f32_e32 v47, v80, v47
	v_add_f32_e32 v47, v81, v47
	v_add_f32_e32 v47, v82, v47
	v_add_f32_e32 v47, v83, v47
	s_waitcnt vmcnt(19)
	v_lshlrev_b32_e32 v34, 16, v104
	v_and_b32_e32 v35, 0xffff0000, v104
	v_lshlrev_b32_e32 v32, 16, v105
	v_and_b32_e32 v33, 0xffff0000, v105
	s_nop 0
	v_pk_mul_f32 v[84:85], v[34:35], v[34:35]
	v_pk_mul_f32 v[86:87], v[32:33], v[32:33]
	v_add_f32_e32 v47, v84, v47
	v_add_f32_e32 v47, v85, v47
	v_add_f32_e32 v47, v86, v47
	v_add_f32_e32 v47, v87, v47
	ds_bpermute_b32 v64, v41, v47
	s_waitcnt lgkmcnt(0)
	v_add_f32_e32 v47, v47, v64
	ds_bpermute_b32 v64, v42, v47
	s_waitcnt lgkmcnt(0)
	v_add_f32_e32 v47, v47, v64
	ds_bpermute_b32 v64, v43, v47
	s_waitcnt lgkmcnt(0)
	v_add_f32_e32 v47, v47, v64
	ds_bpermute_b32 v64, v44, v47
	s_waitcnt lgkmcnt(0)
	v_add_f32_e32 v47, v47, v64
	ds_bpermute_b32 v64, v45, v47
	s_waitcnt lgkmcnt(0)
	v_add_f32_e32 v47, v47, v64
	ds_bpermute_b32 v64, v46, v47
	s_waitcnt lgkmcnt(0)
	v_add_f32_e32 v47, v47, v64
	v_fmamk_f32 v47, v47, 0x3a800000, v163
	v_cmp_gt_f32_e32 vcc, s21, v47
	v_mul_f32_e32 v64, 0x4b800000, v47
	s_waitcnt vmcnt(17)
	v_pk_mul_f32 v[66:67], v[112:113], v[38:39]
	v_cndmask_b32_e32 v47, v47, v64, vcc
	v_rsq_f32_e32 v47, v47
	v_pk_mul_f32 v[70:71], v[114:115], v[56:57]
	v_mul_f32_e32 v64, 0x45800000, v47
	v_cndmask_b32_e32 v68, v47, v64, vcc
	v_pk_mul_f32 v[64:65], v[66:67], v[68:69] op_sel_hi:[1, 0]
	v_pk_fma_f32 v[48:49], v[108:109], v[64:65], v[48:49]
	v_pk_mul_f32 v[52:53], v[70:71], v[68:69] op_sel_hi:[1, 0]
	v_pk_fma_f32 v[50:51], v[110:111], v[52:53], v[50:51]
	global_store_dwordx4 v[36:37], v[48:51], off
	s_nop 1
	s_waitcnt vmcnt(13)
	v_pk_mul_f32 v[8:9], v[132:133], v[8:9]
	v_pk_mul_f32 v[10:11], v[134:135], v[10:11]
	v_pk_mul_f32 v[8:9], v[68:69], v[8:9] op_sel_hi:[0, 1]
	v_pk_mul_f32 v[10:11], v[68:69], v[10:11] op_sel_hi:[0, 1]
	v_pk_fma_f32 v[8:9], v[128:129], v[8:9], v[116:117]
	v_pk_fma_f32 v[10:11], v[130:131], v[10:11], v[118:119]
	global_store_dwordx4 v[36:37], v[8:11], off offset:1024
	s_nop 1
	s_waitcnt vmcnt(12)
; DI void modnorm_store(const float (&x)[16], int lane, const float* g, const float* sc, const float* sh, bf16_t* dst) {
;   float ss = 0.f;
; #pragma unroll
;   for (int i = 0; i < 16; ++i) ss += x[i] * x[i];
;   ss = wave_sum(ss);
;   const float rstd = rsqrtf(ss * (1.0f / 1024.0f) + 1e-6f);
; #pragma unroll
;   for (int j = 0; j < 4; ++j) {
;     const int c = j * 256 + lane * 4;
;     const float4 gg = *(const float4*)(g + c), s1 = *(const float4*)(sc + c), s0 = *(const float4*)(sh + c);
;     store_bf4(dst + c, x[j * 4] * rstd * gg.x * (1.f + s1.x) + s0.x, x[j * 4 + 1] * rstd * gg.y * (1.f + s1.y) + s0.y,
;               x[j * 4 + 2] * rstd * gg.z * (1.f + s1.z) + s0.z, x[j * 4 + 3] * rstd * gg.w * (1.f + s1.w) + s0.w);
;   }
; DI void phase_x1(const Params& p, int hf) {
;     ...
;       const float4 gg = *(const float4*)(p.g_post_mix + c), gt = *(const float4*)(mb + 2048 + c);
;       x[j * 4] += gt.x * m[j * 4] * rstd * gg.x; x[j * 4 + 1] += gt.y * m[j * 4 + 1] * rstd * gg.y;
;       x[j * 4 + 2] += gt.z * m[j * 4 + 2] * rstd * gg.z; x[j * 4 + 3] += gt.w * m[j * 4 + 3] * rstd * gg.w;
;       *(float4*)(outp + (size_t)row * 1024 + c) = make_float4(x[j * 4], x[j * 4 + 1], x[j * 4 + 2], x[j * 4 + 3]);
;     }
;     modnorm_store(x, lane, p.g_pre_ffn, mb + 4096, mb + 3072, h2 + (size_t)row * 1024);
	v_pk_mul_f32 v[4:5], v[140:141], v[4:5]
	s_nop 0
	v_pk_mul_f32 v[4:5], v[68:69], v[4:5] op_sel_hi:[0, 1]
	v_pk_fma_f32 v[4:5], v[136:137], v[4:5], v[120:121]
	v_pk_mul_f32 v[0:1], v[142:143], v[6:7]
	s_nop 0
	v_pk_mul_f32 v[0:1], v[68:69], v[0:1] op_sel_hi:[0, 1]
	v_pk_fma_f32 v[6:7], v[138:139], v[0:1], v[122:123]
	global_store_dwordx4 v[36:37], v[4:7], off offset:2048
	s_nop 1
	v_pk_mul_f32 v[38:39], v[8:9], v[8:9]
	v_pk_mul_f32 v[56:57], v[6:7], v[6:7]
	s_waitcnt vmcnt(11)
	v_pk_mul_f32 v[32:33], v[150:151], v[32:33]
	v_pk_mul_f32 v[34:35], v[148:149], v[34:35]
	v_pk_mul_f32 v[32:33], v[68:69], v[32:33] op_sel_hi:[0, 1]
	v_pk_mul_f32 v[34:35], v[68:69], v[34:35] op_sel_hi:[0, 1]
	v_pk_fma_f32 v[2:3], v[146:147], v[32:33], v[126:127]
	s_mov_b64 s[22:23], 0x3000
	v_pk_fma_f32 v[0:1], v[144:145], v[34:35], v[124:125]
	v_lshl_add_u64 v[34:35], v[30:31], 0, s[22:23]
	v_pk_mul_f32 v[30:31], v[48:49], v[48:49]
	global_store_dwordx4 v[36:37], v[0:3], off offset:3072
	s_nop 1
	v_pk_mul_f32 v[36:37], v[50:51], v[50:51]
	v_add_f32_e32 v30, v30, v31
	v_add_f32_e32 v30, v36, v30
	v_add_f32_e32 v30, v37, v30
	v_add_f32_e32 v30, v38, v30
	v_pk_mul_f32 v[52:53], v[10:11], v[10:11]
	v_add_f32_e32 v30, v39, v30
	v_add_f32_e32 v30, v52, v30
	v_pk_mul_f32 v[54:55], v[4:5], v[4:5]
	v_add_f32_e32 v30, v53, v30
	v_add_f32_e32 v30, v30, v54
	v_add_f32_e32 v30, v55, v30
	v_add_f32_e32 v30, v56, v30
	v_pk_mul_f32 v[58:59], v[0:1], v[0:1]
	v_add_f32_e32 v30, v57, v30
	v_add_f32_e32 v30, v30, v58
	v_lshl_add_u64 v[56:57], v[34:35], 0, v[152:153]
	v_add_f32_e32 v30, v59, v30
	s_nop 0
	s_nop 0
	global_load_dwordx4 v[56:59], v[56:57], off
	v_pk_mul_f32 v[60:61], v[2:3], v[2:3]
	s_nop 0
	v_add_f32_e32 v30, v60, v30
	v_add_f32_e32 v30, v61, v30
	ds_bpermute_b32 v31, v41, v30
	s_waitcnt lgkmcnt(0)
	v_add_f32_e32 v30, v30, v31
	ds_bpermute_b32 v31, v42, v30
	s_waitcnt lgkmcnt(0)
	v_add_f32_e32 v30, v30, v31
	ds_bpermute_b32 v31, v43, v30
	s_waitcnt lgkmcnt(0)
	v_add_f32_e32 v30, v30, v31
	ds_bpermute_b32 v31, v44, v30
	s_waitcnt lgkmcnt(0)
	v_add_f32_e32 v30, v30, v31
	ds_bpermute_b32 v31, v45, v30
	s_waitcnt lgkmcnt(0)
	v_add_f32_e32 v30, v30, v31
	ds_bpermute_b32 v31, v46, v30
	s_waitcnt lgkmcnt(0)
	v_add_f32_e32 v30, v30, v31
	v_fmamk_f32 v30, v30, 0x3a800000, v163
	v_cmp_gt_f32_e32 vcc, s21, v30
	v_mul_f32_e32 v31, 0x4b800000, v30
	s_nop 0
	v_cndmask_b32_e32 v30, v30, v31, vcc
	v_rsq_f32_e32 v30, v30
	s_nop 0
	v_mul_f32_e32 v31, 0x45800000, v30
	v_cndmask_b32_e32 v30, v30, v31, vcc
	v_pk_mul_f32 v[48:49], v[48:49], v[30:31] op_sel_hi:[1, 0]
	v_pk_mul_f32 v[8:9], v[8:9], v[30:31] op_sel_hi:[1, 0]
	v_pk_mul_f32 v[10:11], v[10:11], v[30:31] op_sel_hi:[1, 0]
	v_pk_mul_f32 v[4:5], v[4:5], v[30:31] op_sel_hi:[1, 0]
	v_pk_mul_f32 v[6:7], v[6:7], v[30:31] op_sel_hi:[1, 0]
	v_pk_mul_f32 v[0:1], v[0:1], v[30:31] op_sel_hi:[1, 0]
	v_pk_mul_f32 v[2:3], v[2:3], v[30:31] op_sel_hi:[1, 0]
	s_waitcnt vmcnt(12)
	v_pk_mul_f32 v[36:37], v[188:189], v[48:49]
	s_waitcnt vmcnt(11)
	v_pk_add_f32 v[48:49], v[192:193], 1.0 op_sel_hi:[1, 0]
	v_lshl_add_u64 v[52:53], v[34:35], 0, v[24:25]
	s_waitcnt vmcnt(0)
	v_pk_fma_f32 v[36:37], v[48:49], v[36:37], v[56:57]
	v_pk_mul_f32 v[48:49], v[50:51], v[30:31] op_sel_hi:[1, 0]
	v_cvt_pk_bf16_f32 v36, v36, v37
	v_pk_mul_f32 v[38:39], v[190:191], v[48:49]
	v_pk_add_f32 v[48:49], v[194:195], 1.0 op_sel_hi:[1, 0]
	s_nop 0
	v_pk_fma_f32 v[38:39], v[48:49], v[38:39], v[58:59]
	v_cvt_pk_bf16_f32 v37, v38, v39
	v_add_co_u32_e32 v38, vcc, s1, v16
	s_mov_b32 s1, 0xf4001000
	s_nop 0
	v_addc_co_u32_e32 v39, vcc, -1, v17, vcc
	global_store_dwordx2 v[38:39], v[36:37], off
	s_nop 0
	s_nop 0
	global_load_dwordx4 v[52:55], v[52:53], off
	v_pk_mul_f32 v[8:9], v[8:9], v[200:201]
	v_pk_add_f32 v[36:37], v[204:205], 1.0 op_sel_hi:[1, 0]
	v_pk_mul_f32 v[10:11], v[10:11], v[202:203]
	s_waitcnt vmcnt(0)
	v_pk_fma_f32 v[8:9], v[8:9], v[36:37], v[52:53]
	v_pk_add_f32 v[36:37], v[206:207], 1.0 op_sel_hi:[1, 0]
	v_add_co_u32_e32 v52, vcc, s1, v16
	v_pk_fma_f32 v[10:11], v[10:11], v[36:37], v[54:55]
	v_cvt_pk_bf16_f32 v8, v8, v9
	v_cvt_pk_bf16_f32 v9, v10, v11
	v_addc_co_u32_e32 v53, vcc, -1, v17, vcc
	global_store_dwordx2 v[52:53], v[8:9], off offset:-3584
	v_lshl_add_u64 v[48:49], v[34:35], 0, v[26:27]
	s_nop 0
	s_nop 0
	global_load_dwordx4 v[48:51], v[48:49], off
	v_cmp_lt_i32_e32 vcc, s96, v40
	v_lshl_add_u64 v[16:17], v[16:17], 0, s[84:85]
	s_or_b64 s[24:25], vcc, s[24:25]
	v_pk_mul_f32 v[4:5], v[4:5], v[208:209]
	v_pk_add_f32 v[8:9], v[212:213], 1.0 op_sel_hi:[1, 0]
	v_pk_mul_f32 v[6:7], v[6:7], v[210:211]
	s_waitcnt vmcnt(0)
	v_pk_fma_f32 v[4:5], v[4:5], v[8:9], v[48:49]
	v_pk_add_f32 v[8:9], v[214:215], 1.0 op_sel_hi:[1, 0]
	v_cvt_pk_bf16_f32 v4, v4, v5
	v_pk_fma_f32 v[6:7], v[6:7], v[8:9], v[50:51]
	v_cvt_pk_bf16_f32 v5, v6, v7
	global_store_dwordx2 v[52:53], v[4:5], off offset:-3072
	v_lshl_add_u64 v[32:33], v[34:35], 0, v[28:29]
	s_nop 0
	s_nop 0
	global_load_dwordx4 v[32:35], v[32:33], off
	v_pk_mul_f32 v[0:1], v[0:1], v[220:221]
	v_pk_add_f32 v[4:5], v[224:225], 1.0 op_sel_hi:[1, 0]
	v_pk_mul_f32 v[2:3], v[2:3], v[222:223]
	s_waitcnt vmcnt(0)
	v_pk_fma_f32 v[0:1], v[0:1], v[4:5], v[32:33]
	v_pk_add_f32 v[4:5], v[226:227], 1.0 op_sel_hi:[1, 0]
	v_cvt_pk_bf16_f32 v0, v0, v1
	v_pk_fma_f32 v[2:3], v[2:3], v[4:5], v[34:35]
	s_nop 0
	v_cvt_pk_bf16_f32 v1, v2, v3
	global_store_dwordx2 v[52:53], v[0:1], off offset:-2560
	s_andn2_b64 exec, exec, s[24:25]
	s_cbranch_execnz .LBB0_325

; DI void phase_final(const Params& p, int hf) {
;     ...
;   for (int row = gw; row < HALF_TOK; row += nw) {
;     const int b = (hf == 0 ? 0 : 2) + (row >> lsh);
;     const float* mb = mod + b * 6144;
;     float x[16], m[16];
;     load_row16(outp + (size_t)row * 1024, lane, x);
;     load_row16_bf(fb + (size_t)row * 1024, lane, m);
;     float ss = 0.f;
; #pragma unroll
;     for (int i = 0; i < 16; ++i) ss += m[i] * m[i];
;     ss = wave_sum(ss);
;     const float rstd = rsqrtf(ss * (1.0f / 1024.0f) + 1e-6f);
; #pragma unroll
;     for (int j = 0; j < 4; ++j) {
;       const int c = j * 256 + lane * 4;
;       const float4 gg = *(const float4*)(p.g_post_ffn + c), gt = *(const float4*)(mb + 5120 + c);
;       *(float4*)(outp + (size_t)row * 1024 + c) =
;           make_float4(x[j * 4] + gt.x * m[j * 4] * rstd * gg.x, x[j * 4 + 1] + gt.y * m[j * 4 + 1] * rstd * gg.y,
;                       x[j * 4 + 2] + gt.z * m[j * 4 + 2] * rstd * gg.z, x[j * 4 + 3] + gt.w * m[j * 4 + 3] * rstd * gg.w);
;     }
;   }
.LBB0_376:
	global_load_dwordx2 v[36:37], v[2:3], off offset:-1024
	global_load_dwordx2 v[38:39], v[2:3], off offset:-512
	global_load_dwordx2 v[40:41], v[2:3], off
	global_load_dwordx2 v[42:43], v[2:3], off offset:512
	v_ashrrev_i32_e32 v9, s1, v12
	v_add_u32_e32 v9, s0, v9
	v_mul_lo_u32 v32, v9, s77
	v_ashrrev_i32_e32 v33, 31, v32
	v_lshl_add_u64 v[32:33], v[32:33], 2, s[10:11]
	s_mov_b64 s[22:23], 0x4285000
	v_lshl_add_u64 v[44:45], v[32:33], 0, s[22:23]
	v_lshl_add_u64 v[32:33], v[44:45], 0, v[152:153]
	global_load_dwordx4 v[20:23], v[0:1], off
	global_load_dwordx4 v[24:27], v[4:5], off offset:-2048
	global_load_dwordx4 v[28:31], v[4:5], off offset:-1024
	v_mov_b32_e32 v7, v153
	global_load_dwordx4 v[32:35], v[32:33], off
	v_lshl_add_u64 v[46:47], v[44:45], 0, v[6:7]
	v_mov_b32_e32 v11, v153
	v_add_u32_e32 v12, s58, v12
	v_lshl_add_u64 v[2:3], v[2:3], 0, s[84:85]
	global_load_dwordx4 v[100:103], v[46:47], off
	global_load_dwordx4 v[104:107], v[0:1], off offset:1024
	v_mov_b32_e32 v108, v153
	v_mov_b32_e32 v110, v8
	v_mov_b32_e32 v111, v108
	v_lshl_add_u64 v[112:113], v[44:45], 0, v[110:111]
	global_load_dwordx4 v[116:119], v[4:5], off
	global_load_dwordx4 v[120:123], v[112:113], off
	global_load_dwordx4 v[124:127], v[0:1], off offset:2048
	v_lshl_add_u64 v[114:115], v[44:45], 0, v[10:11]
	global_load_dwordx4 v[128:131], v[4:5], off offset:1024
	global_load_dwordx4 v[132:135], v[114:115], off
	global_load_dwordx4 v[136:139], v[0:1], off offset:3072
	s_waitcnt vmcnt(15)
	v_lshlrev_b32_e32 v48, 16, v36
	v_and_b32_e32 v49, 0xffff0000, v36
	v_lshlrev_b32_e32 v36, 16, v37
	v_and_b32_e32 v37, 0xffff0000, v37
	v_pk_mul_f32 v[56:57], v[48:49], v[48:49]
	v_pk_mul_f32 v[58:59], v[36:37], v[36:37]
	v_add_f32_e32 v7, v56, v57
	s_waitcnt vmcnt(14)
	v_lshlrev_b32_e32 v50, 16, v38
	v_and_b32_e32 v51, 0xffff0000, v38
	v_add_f32_e32 v7, v7, v58
	v_pk_mul_f32 v[60:61], v[50:51], v[50:51]
	v_add_f32_e32 v7, v59, v7
	v_lshlrev_b32_e32 v38, 16, v39
	v_and_b32_e32 v39, 0xffff0000, v39
	v_add_f32_e32 v7, v60, v7
	v_pk_mul_f32 v[62:63], v[38:39], v[38:39]
	v_add_f32_e32 v7, v61, v7
	s_waitcnt vmcnt(13)
	v_lshlrev_b32_e32 v52, 16, v40
	v_and_b32_e32 v53, 0xffff0000, v40
	v_add_f32_e32 v7, v62, v7
	v_pk_mul_f32 v[64:65], v[52:53], v[52:53]
	v_add_f32_e32 v7, v63, v7
	v_lshlrev_b32_e32 v40, 16, v41
	v_and_b32_e32 v41, 0xffff0000, v41
	v_add_f32_e32 v7, v64, v7
	v_pk_mul_f32 v[66:67], v[40:41], v[40:41]
	v_add_f32_e32 v7, v65, v7
	s_waitcnt vmcnt(12)
	v_lshlrev_b32_e32 v54, 16, v42
	v_and_b32_e32 v55, 0xffff0000, v42
	v_add_f32_e32 v7, v66, v7
	v_pk_mul_f32 v[68:69], v[54:55], v[54:55]
	v_add_f32_e32 v7, v67, v7
	v_lshlrev_b32_e32 v42, 16, v43
	v_and_b32_e32 v43, 0xffff0000, v43
	v_add_f32_e32 v7, v68, v7
	v_pk_mul_f32 v[70:71], v[42:43], v[42:43]
	v_add_f32_e32 v7, v69, v7
	v_add_f32_e32 v7, v70, v7
	v_add_f32_e32 v7, v71, v7
	ds_bpermute_b32 v9, v13, v7
	s_waitcnt vmcnt(8)
	v_pk_mul_f32 v[32:33], v[32:33], v[48:49]
	v_pk_mul_f32 v[34:35], v[34:35], v[36:37]
	s_waitcnt lgkmcnt(0)
	v_add_f32_e32 v7, v7, v9
	ds_bpermute_b32 v9, v14, v7
	s_waitcnt lgkmcnt(0)
	v_add_f32_e32 v7, v7, v9
	ds_bpermute_b32 v9, v15, v7
	s_waitcnt lgkmcnt(0)
	v_add_f32_e32 v7, v7, v9
	ds_bpermute_b32 v9, v16, v7
	s_waitcnt lgkmcnt(0)
	v_add_f32_e32 v7, v7, v9
	ds_bpermute_b32 v9, v17, v7
	s_waitcnt lgkmcnt(0)
	v_add_f32_e32 v7, v7, v9
	ds_bpermute_b32 v9, v18, v7
	s_waitcnt lgkmcnt(0)
	v_add_f32_e32 v7, v7, v9
	v_fmamk_f32 v7, v7, 0x3a800000, v163
	v_mul_f32_e32 v9, 0x4b800000, v7
	v_cmp_gt_f32_e32 vcc, s21, v7
	s_nop 1
	v_cndmask_b32_e32 v7, v7, v9, vcc
	v_rsq_f32_e32 v7, v7
	s_nop 0
	v_mul_f32_e32 v9, 0x45800000, v7
	v_cndmask_b32_e32 v36, v7, v9, vcc
	v_pk_mul_f32 v[32:33], v[32:33], v[36:37] op_sel_hi:[1, 0]
	v_pk_mul_f32 v[34:35], v[34:35], v[36:37] op_sel_hi:[1, 0]
	v_pk_fma_f32 v[20:21], v[20:21], v[32:33], v[24:25]
	v_pk_fma_f32 v[22:23], v[22:23], v[34:35], v[26:27]
	global_store_dwordx4 v[4:5], v[20:23], off offset:-2048
	s_nop 1
	s_nop 0
	v_cmp_lt_i32_e32 vcc, s96, v12
	s_or_b64 s[4:5], vcc, s[4:5]
	s_waitcnt vmcnt(8)
	v_pk_mul_f32 v[20:21], v[100:101], v[50:51]
	v_pk_mul_f32 v[22:23], v[102:103], v[38:39]
	v_pk_mul_f32 v[20:21], v[36:37], v[20:21] op_sel_hi:[0, 1]
	v_pk_mul_f32 v[22:23], v[36:37], v[22:23] op_sel_hi:[0, 1]
	s_waitcnt vmcnt(7)
	v_pk_fma_f32 v[20:21], v[104:105], v[20:21], v[28:29]
	v_pk_fma_f32 v[22:23], v[106:107], v[22:23], v[30:31]
	global_store_dwordx4 v[4:5], v[20:23], off offset:-1024
	s_nop 1
	s_nop 0
	s_waitcnt vmcnt(6)
	v_pk_mul_f32 v[20:21], v[120:121], v[52:53]
	v_pk_mul_f32 v[22:23], v[122:123], v[40:41]
	v_pk_mul_f32 v[20:21], v[36:37], v[20:21] op_sel_hi:[0, 1]
	v_pk_mul_f32 v[22:23], v[36:37], v[22:23] op_sel_hi:[0, 1]
	s_waitcnt vmcnt(5)
	v_pk_fma_f32 v[20:21], v[124:125], v[20:21], v[116:117]
	v_pk_fma_f32 v[22:23], v[126:127], v[22:23], v[118:119]
	global_store_dwordx4 v[4:5], v[20:23], off
	s_nop 1
	s_nop 0
	s_waitcnt vmcnt(4)
	v_pk_mul_f32 v[20:21], v[132:133], v[54:55]
	v_pk_mul_f32 v[22:23], v[134:135], v[42:43]
	v_pk_mul_f32 v[20:21], v[36:37], v[20:21] op_sel_hi:[0, 1]
	v_pk_mul_f32 v[22:23], v[36:37], v[22:23] op_sel_hi:[0, 1]
	s_waitcnt vmcnt(3)
	v_pk_fma_f32 v[20:21], v[136:137], v[20:21], v[128:129]
	v_pk_fma_f32 v[22:23], v[138:139], v[22:23], v[130:131]
	global_store_dwordx4 v[4:5], v[20:23], off offset:1024
	s_nop 1
	v_lshl_add_u64 v[4:5], v[4:5], 0, s[90:91]
	s_andn2_b64 exec, exec, s[4:5]
	s_cbranch_execnz .LBB0_376
